# gemm1 partial 11th tile round deferred into start of branches phase + relaxed first-iteration waits
# baseline (speedup 1.0000x reference)
; template <class Epi>
; __device__ __forceinline__ void gemm_phase(LAS unsigned char* lds, const Gemm g, const Order& S, const Epi& E) {
;     ...
;     for (;;) {
;         const bool has_next = S.next(ui + 1, nxt);
;         const char* nA = has_next ? (const char*)(g.A + (size_t)nxt.g * g.gA) + (size_t)nxt.pm * tstepA : cA; const char* nB = has_next ? (const char*)(g.Bt + (size_t)nxt.g * g.gB) + (size_t)nxt.pn * tstepB : cB;
.LBB0_26:
	s_andn2_b64 vcc, exec, s[36:37]
	s_mov_b32 s14, s11
	s_mov_b32 s13, s12
	s_mov_b64 s[44:45], s[40:41]
	s_mov_b64 s[42:43], s[0:1]
	s_cbranch_vccz .LBB0_46
	s_bitset1_b32 s100, 1

; #define PG8_STAGE(bufoff, gbase, voff) do { _Pragma("unroll") for (int _i = 0; _i < 2; ++_i) \
;         __builtin_amdgcn_global_load_lds((const unsigned*)((const char*)(gbase) + (voff)[_i]), (LAS unsigned*)(lds + (bufoff) + ldsw + _i * 8192), 16, 0, 0); } while (0)
; #define PG8_LDA(dst, b, h) do { _Pragma("unroll") for (int m = 0; m < 4; ++m) _Pragma("unroll") for (int k = 0; k < 2; ++k) dst[m][k] = *(const LAS bf16x8*)(lds + PG8_SA(b, h) + aoff + m * 2048 + k * 1024); } while (0)
; #define PG8_LDB(dst, b, h) do { _Pragma("unroll") for (int n = 0; n < 2; ++n) _Pragma("unroll") for (int k = 0; k < 2; ++k) dst[n][k] = *(const LAS bf16x8*)(lds + PG8_SB(b, h) + boff + n * 2048 + k * 1024); } while (0)
; #define PG8_MMA(ai, bj, At, Bt) do { __builtin_amdgcn_s_setprio(1); _Pragma("unroll") for (int m = 0; m < 4; ++m) _Pragma("unroll") for (int n = 0; n < 2; ++n) _Pragma("unroll") for (int k = 0; k < 2; ++k) \
;         acc[ai][bj][m][n] = __builtin_amdgcn_mfma_f32_16x16x32_bf16(Bt[n][k], At[m][k], acc[ai][bj][m][n], 0, 0, 0); __builtin_amdgcn_s_setprio(0); } while (0)
; #define PG8_WAIT_V(n) asm volatile("s_waitcnt vmcnt(" #n ")" ::: "memory")
; #define PG8_WAIT_L(n) asm volatile("s_waitcnt lgkmcnt(" #n ")" ::: "memory")
; #define PG8_BAR __builtin_amdgcn_s_barrier()
; #define PG8_SCHED __builtin_amdgcn_sched_barrier(0)
; template <class Epi>
; __device__ __forceinline__ void gemm_phase(LAS unsigned char* lds, const Gemm g, const Order& S, const Epi& E) {
;     ...
;         for (int t = 0; t < nt; t += 2) {
;             const bool last = (t == nt - 2);
;             const char* a1 = cA + (size_t)(t + 1) * kstep;
;             const char* a2 = last ? nA : cA + (size_t)(t + 2) * kstep; const char* b2 = last ? nB : cB + (size_t)(t + 2) * kstep;
;             const char* a3 = a2 + kstep; const char* b3 = b2 + kstep;
;             PG8_LDB(B0, 0, 0); PG8_LDB(B1, 0, 1); PG8_SCHED; PG8_LDA(At, 0, 0); PG8_STAGE(PG8_SA(1, 1), a1 + hstepA, voffA);
;             PG8_WAIT_V(8); PG8_WAIT_L(0); PG8_BAR; PG8_MMA(0, 0, At, B0); PG8_MMA(0, 1, At, B1); PG8_BAR; PG8_SCHED;
.LBB0_38:
	s_add_u32 s44, s42, 0x100
	s_addc_u32 s45, s43, 0
	s_add_i32 s18, 0, 0x10000
	s_cmp_eq_u32 s17, 40
	s_cselect_b32 s51, s1, s45
	s_cselect_b32 s50, s0, s44
	v_add_u32_e32 v140, s18, v143
	s_cselect_b32 s47, s41, s16
	s_cselect_b32 s46, s40, s15
	s_add_i32 s20, 0, 0x14000
	ds_read_b128 v[146:149], v140
	ds_read_b128 v[150:153], v140 offset:1024
	ds_read_b128 v[154:157], v140 offset:2048
	ds_read_b128 v[158:161], v140 offset:3072
	v_add_u32_e32 v140, s20, v143
	ds_read_b128 v[162:165], v140
	ds_read_b128 v[166:169], v140 offset:1024
	ds_read_b128 v[170:173], v140 offset:2048
	ds_read_b128 v[174:177], v140 offset:3072
	v_lshl_add_u64 v[140:141], s[42:43], 0, v[136:137]
	s_add_i32 m0, s4, 0xc000
	ds_read_b128 v[178:181], v145
	ds_read_b128 v[182:185], v145 offset:1024
	ds_read_b128 v[186:189], v145 offset:2048
	ds_read_b128 v[190:193], v145 offset:3072
	ds_read_b128 v[204:207], v145 offset:4096
	ds_read_b128 v[208:211], v145 offset:5120
	ds_read_b128 v[212:215], v145 offset:6144
	ds_read_b128 v[216:219], v145 offset:7168
	global_load_lds_dwordx4 v[140:141], off
	v_lshl_add_u64 v[140:141], s[42:43], 0, v[138:139]
	s_add_i32 m0, s4, 0xe000
	s_nop 0
	global_load_lds_dwordx4 v[140:141], off
	s_bitcmp1_b32 s100, 1
	s_cbranch_scc1 .Lxr1_LBB038
	s_waitcnt vmcnt(8)
	s_branch .Lxb1_LBB038

; #define PG8_STAGE(bufoff, gbase, voff) do { _Pragma("unroll") for (int _i = 0; _i < 2; ++_i) \
;         __builtin_amdgcn_global_load_lds((const unsigned*)((const char*)(gbase) + (voff)[_i]), (LAS unsigned*)(lds + (bufoff) + ldsw + _i * 8192), 16, 0, 0); } while (0)
; #define PG8_LDA(dst, b, h) do { _Pragma("unroll") for (int m = 0; m < 4; ++m) _Pragma("unroll") for (int k = 0; k < 2; ++k) dst[m][k] = *(const LAS bf16x8*)(lds + PG8_SA(b, h) + aoff + m * 2048 + k * 1024); } while (0)
; #define PG8_MMA(ai, bj, At, Bt) do { __builtin_amdgcn_s_setprio(1); _Pragma("unroll") for (int m = 0; m < 4; ++m) _Pragma("unroll") for (int n = 0; n < 2; ++n) _Pragma("unroll") for (int k = 0; k < 2; ++k) \
;         acc[ai][bj][m][n] = __builtin_amdgcn_mfma_f32_16x16x32_bf16(Bt[n][k], At[m][k], acc[ai][bj][m][n], 0, 0, 0); __builtin_amdgcn_s_setprio(0); } while (0)
; #define PG8_WAIT_V(n) asm volatile("s_waitcnt vmcnt(" #n ")" ::: "memory")
; #define PG8_WAIT_L(n) asm volatile("s_waitcnt lgkmcnt(" #n ")" ::: "memory")
; #define PG8_BAR __builtin_amdgcn_s_barrier()
; #define PG8_SCHED __builtin_amdgcn_sched_barrier(0)
; template <class Epi>
; __device__ __forceinline__ void gemm_phase(LAS unsigned char* lds, const Gemm g, const Order& S, const Epi& E) {
;     ...
;             PG8_WAIT_V(8); PG8_WAIT_L(0); PG8_BAR; PG8_MMA(0, 0, At, B0); PG8_MMA(0, 1, At, B1); PG8_BAR; PG8_SCHED;
;             PG8_LDA(At, 0, 1); PG8_STAGE(PG8_SB(0, 0), b2, voffB); PG8_STAGE(PG8_SB(0, 1), b2 + hstepB, voffB); PG8_STAGE(PG8_SA(0, 0), a2, voffA);
;             PG8_WAIT_V(8); PG8_WAIT_L(0); PG8_BAR; PG8_MMA(1, 0, At, B0); PG8_MMA(1, 1, At, B1); PG8_BAR; PG8_SCHED;
.Lxb1_LBB038:
	s_waitcnt lgkmcnt(0)
	s_barrier
	s_setprio 1
	s_waitcnt lgkmcnt(0)
	v_mfma_f32_16x16x32_bf16 v[126:129], v[146:149], v[178:181], v[126:129]
	v_mfma_f32_16x16x32_bf16 v[122:125], v[154:157], v[178:181], v[122:125]
	v_mfma_f32_16x16x32_bf16 v[114:117], v[146:149], v[186:189], v[114:117]
	v_mfma_f32_16x16x32_bf16 v[106:109], v[154:157], v[186:189], v[106:109]
	v_mfma_f32_16x16x32_bf16 v[98:101], v[146:149], v[204:207], v[98:101]
	v_mfma_f32_16x16x32_bf16 v[90:93], v[154:157], v[204:207], v[90:93]
	v_mfma_f32_16x16x32_bf16 v[82:85], v[146:149], v[212:215], v[82:85]
	v_mfma_f32_16x16x32_bf16 v[74:77], v[154:157], v[212:215], v[74:77]
	v_mfma_f32_16x16x32_bf16 v[126:129], v[150:153], v[182:185], v[126:129]
	v_mfma_f32_16x16x32_bf16 v[122:125], v[158:161], v[182:185], v[122:125]
	v_mfma_f32_16x16x32_bf16 v[114:117], v[150:153], v[190:193], v[114:117]
	v_mfma_f32_16x16x32_bf16 v[106:109], v[158:161], v[190:193], v[106:109]
	v_mfma_f32_16x16x32_bf16 v[98:101], v[150:153], v[208:211], v[98:101]
	v_mfma_f32_16x16x32_bf16 v[90:93], v[158:161], v[208:211], v[90:93]
	v_mfma_f32_16x16x32_bf16 v[82:85], v[150:153], v[216:219], v[82:85]
	v_mfma_f32_16x16x32_bf16 v[74:77], v[158:161], v[216:219], v[74:77]
	s_setprio 0
	s_setprio 1
	v_mfma_f32_16x16x32_bf16 v[118:121], v[162:165], v[178:181], v[118:121]
	v_mfma_f32_16x16x32_bf16 v[110:113], v[170:173], v[178:181], v[110:113]
	v_mfma_f32_16x16x32_bf16 v[102:105], v[162:165], v[186:189], v[102:105]
	v_mfma_f32_16x16x32_bf16 v[94:97], v[170:173], v[186:189], v[94:97]
	v_mfma_f32_16x16x32_bf16 v[86:89], v[162:165], v[204:207], v[86:89]
	v_mfma_f32_16x16x32_bf16 v[78:81], v[170:173], v[204:207], v[78:81]
	v_mfma_f32_16x16x32_bf16 v[70:73], v[162:165], v[212:215], v[70:73]
	v_mfma_f32_16x16x32_bf16 v[66:69], v[170:173], v[212:215], v[66:69]
	v_mfma_f32_16x16x32_bf16 v[118:121], v[166:169], v[182:185], v[118:121]
	v_mfma_f32_16x16x32_bf16 v[110:113], v[174:177], v[182:185], v[110:113]
	v_mfma_f32_16x16x32_bf16 v[102:105], v[166:169], v[190:193], v[102:105]
	v_mfma_f32_16x16x32_bf16 v[94:97], v[174:177], v[190:193], v[94:97]
	v_mfma_f32_16x16x32_bf16 v[86:89], v[166:169], v[208:211], v[86:89]
	v_mfma_f32_16x16x32_bf16 v[78:81], v[174:177], v[208:211], v[78:81]
	v_mfma_f32_16x16x32_bf16 v[70:73], v[166:169], v[216:219], v[70:73]
	v_mfma_f32_16x16x32_bf16 v[66:69], v[174:177], v[216:219], v[66:69]
	s_setprio 0
	s_barrier
	s_add_i32 s18, s18, s2
	v_lshl_add_u64 v[140:141], s[46:47], 0, v[194:195]
	s_mov_b32 m0, s18
	ds_read_b128 v[178:181], v145 offset:16384
	ds_read_b128 v[182:185], v145 offset:17408
	ds_read_b128 v[186:189], v145 offset:18432
	ds_read_b128 v[190:193], v145 offset:19456
	ds_read_b128 v[204:207], v145 offset:20480
	ds_read_b128 v[208:211], v145 offset:21504
	ds_read_b128 v[212:215], v145 offset:22528
	ds_read_b128 v[216:219], v145 offset:23552
	global_load_lds_dwordx4 v[140:141], off
	s_add_i32 m0, s18, 0x2000
	s_add_u32 s18, s46, 0xb0000
	v_lshl_add_u64 v[200:201], s[46:47], 0, v[130:131]
	s_addc_u32 s19, s47, 0
	s_add_i32 s20, s20, s2
	global_load_lds_dwordx4 v[200:201], off
	v_lshl_add_u64 v[220:221], s[18:19], 0, v[194:195]
	s_mov_b32 m0, s20
	v_lshl_add_u64 v[222:223], s[50:51], 0, v[132:133]
	global_load_lds_dwordx4 v[220:221], off
	v_lshl_add_u64 v[220:221], s[18:19], 0, v[130:131]
	s_add_i32 m0, s20, 0x2000
	s_nop 0
	global_load_lds_dwordx4 v[220:221], off
	v_lshl_add_u64 v[220:221], s[50:51], 0, v[134:135]
	s_mov_b32 m0, s4
	s_nop 0
	global_load_lds_dwordx4 v[220:221], off
	s_mov_b32 m0, s5
	s_nop 0
	global_load_lds_dwordx4 v[222:223], off
	s_bitcmp1_b32 s100, 1
	s_cbranch_scc1 .Lxr2_LBB038
	s_waitcnt vmcnt(8)
	s_branch .Lxb2_LBB038
.Lxr2_LBB038:
	s_waitcnt vmcnt(24)
	s_bitset0_b32 s100, 1

; template <class Epi>
; __device__ __forceinline__ void gemm_phase(LAS unsigned char* lds, const Gemm g, const Order& S, const Epi& E) {
;     ...
;     for (;;) {
;         const bool has_next = S.next(ui + 1, nxt);
;         const char* nA = has_next ? (const char*)(g.A + (size_t)nxt.g * g.gA) + (size_t)nxt.pm * tstepA : cA; const char* nB = has_next ? (const char*)(g.Bt + (size_t)nxt.g * g.gB) + (size_t)nxt.pn * tstepB : cB;
.LBB0_67:
	s_andn2_b64 vcc, exec, s[30:31]
	s_mov_b32 s7, s80
	s_mov_b32 s30, s82
	s_mov_b64 s[48:49], s[50:51]
	s_mov_b64 s[46:47], s[90:91]
	s_cbranch_vccz .LBB0_91
	s_bitset1_b32 s100, 1

; #define PG8_STAGE(bufoff, gbase, voff) do { _Pragma("unroll") for (int _i = 0; _i < 2; ++_i) \
;         __builtin_amdgcn_global_load_lds((const unsigned*)((const char*)(gbase) + (voff)[_i]), (LAS unsigned*)(lds + (bufoff) + ldsw + _i * 8192), 16, 0, 0); } while (0)
; #define PG8_LDA(dst, b, h) do { _Pragma("unroll") for (int m = 0; m < 4; ++m) _Pragma("unroll") for (int k = 0; k < 2; ++k) dst[m][k] = *(const LAS bf16x8*)(lds + PG8_SA(b, h) + aoff + m * 2048 + k * 1024); } while (0)
; #define PG8_LDB(dst, b, h) do { _Pragma("unroll") for (int n = 0; n < 2; ++n) _Pragma("unroll") for (int k = 0; k < 2; ++k) dst[n][k] = *(const LAS bf16x8*)(lds + PG8_SB(b, h) + boff + n * 2048 + k * 1024); } while (0)
; #define PG8_MMA(ai, bj, At, Bt) do { __builtin_amdgcn_s_setprio(1); _Pragma("unroll") for (int m = 0; m < 4; ++m) _Pragma("unroll") for (int n = 0; n < 2; ++n) _Pragma("unroll") for (int k = 0; k < 2; ++k) \
;         acc[ai][bj][m][n] = __builtin_amdgcn_mfma_f32_16x16x32_bf16(Bt[n][k], At[m][k], acc[ai][bj][m][n], 0, 0, 0); __builtin_amdgcn_s_setprio(0); } while (0)
; #define PG8_WAIT_V(n) asm volatile("s_waitcnt vmcnt(" #n ")" ::: "memory")
; #define PG8_WAIT_L(n) asm volatile("s_waitcnt lgkmcnt(" #n ")" ::: "memory")
; #define PG8_BAR __builtin_amdgcn_s_barrier()
; #define PG8_SCHED __builtin_amdgcn_sched_barrier(0)
; template <class Epi>
; __device__ __forceinline__ void gemm_phase(LAS unsigned char* lds, const Gemm g, const Order& S, const Epi& E) {
;     ...
;         for (int t = 0; t < nt; t += 2) {
;             const bool last = (t == nt - 2);
;             const char* a1 = cA + (size_t)(t + 1) * kstep;
;             const char* a2 = last ? nA : cA + (size_t)(t + 2) * kstep; const char* b2 = last ? nB : cB + (size_t)(t + 2) * kstep;
;             const char* a3 = a2 + kstep; const char* b3 = b2 + kstep;
;             PG8_LDB(B0, 0, 0); PG8_LDB(B1, 0, 1); PG8_SCHED; PG8_LDA(At, 0, 0); PG8_STAGE(PG8_SA(1, 1), a1 + hstepA, voffA);
;             PG8_WAIT_V(8); PG8_WAIT_L(0); PG8_BAR; PG8_MMA(0, 0, At, B0); PG8_MMA(0, 1, At, B1); PG8_BAR; PG8_SCHED;
.LBB0_71:
	s_add_u32 s15, s46, 0xfffc0080
	s_addc_u32 s16, s47, -1
	s_add_i32 s17, 0, 0x10000
	s_cmp_eq_u32 s14, 12
	s_cselect_b32 s49, s8, s16
	s_cselect_b32 s48, s9, s15
	s_cselect_b32 vcc_hi, s10, s13
	s_cselect_b32 vcc_lo, s11, s12
	s_add_i32 s15, 0, 0x14000
	v_add_u32_e32 v78, s17, v205
	v_add_u32_e32 v102, s15, v205
	ds_read_b128 v[66:69], v78
	ds_read_b128 v[70:73], v78 offset:1024
	ds_read_b128 v[74:77], v78 offset:2048
	ds_read_b128 v[78:81], v78 offset:3072
	ds_read_b128 v[90:93], v102
	ds_read_b128 v[94:97], v102 offset:1024
	ds_read_b128 v[98:101], v102 offset:2048
	ds_read_b128 v[102:105], v102 offset:3072
	v_lshl_add_u64 v[192:193], s[46:47], 0, v[188:189]
	s_add_i32 m0, s20, 0xc000
	ds_read_b128 v[162:165], v208
	ds_read_b128 v[166:169], v208 offset:1024
	ds_read_b128 v[170:173], v208 offset:2048
	ds_read_b128 v[174:177], v208 offset:3072
	ds_read_b128 v[210:213], v208 offset:4096
	ds_read_b128 v[214:217], v208 offset:5120
	ds_read_b128 v[218:221], v208 offset:6144
	ds_read_b128 v[222:225], v208 offset:7168
	global_load_lds_dwordx4 v[192:193], off
	v_lshl_add_u64 v[192:193], s[46:47], 0, v[190:191]
	s_add_i32 m0, s20, 0xe000
	s_nop 0
	global_load_lds_dwordx4 v[192:193], off
	s_bitcmp1_b32 s100, 1
	s_cbranch_scc1 .Lxr1_LBB071
	s_waitcnt vmcnt(8)
	s_branch .Lxb1_LBB071

; #define PG8_STAGE(bufoff, gbase, voff) do { _Pragma("unroll") for (int _i = 0; _i < 2; ++_i) \
;         __builtin_amdgcn_global_load_lds((const unsigned*)((const char*)(gbase) + (voff)[_i]), (LAS unsigned*)(lds + (bufoff) + ldsw + _i * 8192), 16, 0, 0); } while (0)
; #define PG8_LDA(dst, b, h) do { _Pragma("unroll") for (int m = 0; m < 4; ++m) _Pragma("unroll") for (int k = 0; k < 2; ++k) dst[m][k] = *(const LAS bf16x8*)(lds + PG8_SA(b, h) + aoff + m * 2048 + k * 1024); } while (0)
; #define PG8_MMA(ai, bj, At, Bt) do { __builtin_amdgcn_s_setprio(1); _Pragma("unroll") for (int m = 0; m < 4; ++m) _Pragma("unroll") for (int n = 0; n < 2; ++n) _Pragma("unroll") for (int k = 0; k < 2; ++k) \
;         acc[ai][bj][m][n] = __builtin_amdgcn_mfma_f32_16x16x32_bf16(Bt[n][k], At[m][k], acc[ai][bj][m][n], 0, 0, 0); __builtin_amdgcn_s_setprio(0); } while (0)
; #define PG8_WAIT_V(n) asm volatile("s_waitcnt vmcnt(" #n ")" ::: "memory")
; #define PG8_WAIT_L(n) asm volatile("s_waitcnt lgkmcnt(" #n ")" ::: "memory")
; #define PG8_BAR __builtin_amdgcn_s_barrier()
; #define PG8_SCHED __builtin_amdgcn_sched_barrier(0)
; template <class Epi>
; __device__ __forceinline__ void gemm_phase(LAS unsigned char* lds, const Gemm g, const Order& S, const Epi& E) {
;     ...
;             PG8_WAIT_V(8); PG8_WAIT_L(0); PG8_BAR; PG8_MMA(0, 0, At, B0); PG8_MMA(0, 1, At, B1); PG8_BAR; PG8_SCHED;
;             PG8_LDA(At, 0, 1); PG8_STAGE(PG8_SB(0, 0), b2, voffB); PG8_STAGE(PG8_SB(0, 1), b2 + hstepB, voffB); PG8_STAGE(PG8_SA(0, 0), a2, voffA);
;             PG8_WAIT_V(8); PG8_WAIT_L(0); PG8_BAR; PG8_MMA(1, 0, At, B0); PG8_MMA(1, 1, At, B1); PG8_BAR; PG8_SCHED;
.Lxb1_LBB071:
	s_waitcnt lgkmcnt(0)
	s_barrier
	s_setprio 1
	s_waitcnt lgkmcnt(0)
	v_mfma_f32_16x16x32_bf16 v[150:153], v[66:69], v[162:165], v[150:153]
	v_mfma_f32_16x16x32_bf16 v[146:149], v[74:77], v[162:165], v[146:149]
	v_mfma_f32_16x16x32_bf16 v[134:137], v[66:69], v[170:173], v[134:137]
	v_mfma_f32_16x16x32_bf16 v[130:133], v[74:77], v[170:173], v[130:133]
	v_mfma_f32_16x16x32_bf16 v[118:121], v[66:69], v[210:213], v[118:121]
	v_mfma_f32_16x16x32_bf16 v[114:117], v[74:77], v[210:213], v[114:117]
	v_mfma_f32_16x16x32_bf16 v[110:113], v[66:69], v[218:221], v[110:113]
	v_mfma_f32_16x16x32_bf16 v[106:109], v[74:77], v[218:221], v[106:109]
	v_mfma_f32_16x16x32_bf16 v[150:153], v[70:73], v[166:169], v[150:153]
	v_mfma_f32_16x16x32_bf16 v[146:149], v[78:81], v[166:169], v[146:149]
	v_mfma_f32_16x16x32_bf16 v[134:137], v[70:73], v[174:177], v[134:137]
	v_mfma_f32_16x16x32_bf16 v[130:133], v[78:81], v[174:177], v[130:133]
	v_mfma_f32_16x16x32_bf16 v[118:121], v[70:73], v[214:217], v[118:121]
	v_mfma_f32_16x16x32_bf16 v[114:117], v[78:81], v[214:217], v[114:117]
	v_mfma_f32_16x16x32_bf16 v[110:113], v[70:73], v[222:225], v[110:113]
	v_mfma_f32_16x16x32_bf16 v[106:109], v[78:81], v[222:225], v[106:109]
	s_setprio 0
	s_setprio 1
	v_mfma_f32_16x16x32_bf16 v[154:157], v[90:93], v[162:165], v[154:157]
	v_mfma_f32_16x16x32_bf16 v[158:161], v[98:101], v[162:165], v[158:161]
	v_mfma_f32_16x16x32_bf16 v[142:145], v[90:93], v[170:173], v[142:145]
	v_mfma_f32_16x16x32_bf16 v[138:141], v[98:101], v[170:173], v[138:141]
	v_mfma_f32_16x16x32_bf16 v[126:129], v[90:93], v[210:213], v[126:129]
	v_mfma_f32_16x16x32_bf16 v[122:125], v[98:101], v[210:213], v[122:125]
	v_mfma_f32_16x16x32_bf16 v[86:89], v[90:93], v[218:221], v[86:89]
	v_mfma_f32_16x16x32_bf16 v[82:85], v[98:101], v[218:221], v[82:85]
	v_mfma_f32_16x16x32_bf16 v[154:157], v[94:97], v[166:169], v[154:157]
	v_mfma_f32_16x16x32_bf16 v[158:161], v[102:105], v[166:169], v[158:161]
	v_mfma_f32_16x16x32_bf16 v[142:145], v[94:97], v[174:177], v[142:145]
	v_mfma_f32_16x16x32_bf16 v[138:141], v[102:105], v[174:177], v[138:141]
	v_mfma_f32_16x16x32_bf16 v[126:129], v[94:97], v[214:217], v[126:129]
	v_mfma_f32_16x16x32_bf16 v[122:125], v[102:105], v[214:217], v[122:125]
	v_mfma_f32_16x16x32_bf16 v[86:89], v[94:97], v[222:225], v[86:89]
	v_mfma_f32_16x16x32_bf16 v[82:85], v[102:105], v[222:225], v[82:85]
	s_setprio 0
	s_barrier
	s_add_i32 s16, s17, s2
	v_lshl_add_u64 v[192:193], vcc, 0, v[194:195]
	s_mov_b32 m0, s16
	ds_read_b128 v[162:165], v208 offset:16384
	ds_read_b128 v[166:169], v208 offset:17408
	ds_read_b128 v[170:173], v208 offset:18432
	ds_read_b128 v[174:177], v208 offset:19456
	ds_read_b128 v[210:213], v208 offset:20480
	ds_read_b128 v[214:217], v208 offset:21504
	ds_read_b128 v[218:221], v208 offset:22528
	ds_read_b128 v[222:225], v208 offset:23552
	global_load_lds_dwordx4 v[192:193], off
	s_add_i32 m0, s16, 0x2000
	s_add_u32 s16, vcc_lo, 0x40000
	v_lshl_add_u64 v[200:201], vcc, 0, v[178:179]
	s_addc_u32 s17, vcc_hi, 0
	s_add_i32 s15, s15, s2
	global_load_lds_dwordx4 v[200:201], off
	v_lshl_add_u64 v[226:227], s[16:17], 0, v[194:195]
	s_mov_b32 m0, s15
	v_lshl_add_u64 v[228:229], s[48:49], 0, v[180:181]
	global_load_lds_dwordx4 v[226:227], off
	v_lshl_add_u64 v[226:227], s[16:17], 0, v[178:179]
	s_add_i32 m0, s15, 0x2000
	s_nop 0
	global_load_lds_dwordx4 v[226:227], off
	v_lshl_add_u64 v[226:227], s[48:49], 0, v[182:183]
	s_mov_b32 m0, s20
	s_nop 0
	global_load_lds_dwordx4 v[226:227], off
	s_mov_b32 m0, s88
	s_nop 0
	global_load_lds_dwordx4 v[228:229], off
	s_bitcmp1_b32 s100, 1
	s_cbranch_scc1 .Lxr2_LBB071
	s_waitcnt vmcnt(8)
	s_branch .Lxb2_LBB071
.Lxr2_LBB071:
	s_waitcnt vmcnt(15)
	s_bitset0_b32 s100, 1

; __device__ __forceinline__ int get_tid() { int t = threadIdx.x; asm volatile("" : "+v"(t)); return t; }
; #define PG8_STAGE(bufoff, gbase, voff) do { _Pragma("unroll") for (int _i = 0; _i < 2; ++_i) \
;         __builtin_amdgcn_global_load_lds((const unsigned*)((const char*)(gbase) + (voff)[_i]), (LAS unsigned*)(lds + (bufoff) + ldsw + _i * 8192), 16, 0, 0); } while (0)
; #define PG8_BAR __builtin_amdgcn_s_barrier()
; template <class Epi>
; __device__ __forceinline__ void gemm_phase(LAS unsigned char* lds, const Gemm g, const Order& S, const Epi& E) {
;     const int tid = get_tid(), wid = __builtin_amdgcn_readfirstlane(tid >> 6), lane = tid & 63, wr = wid >> 2, wc = wid & 3, fr = lane & 15, fq = lane >> 4;
;     const int K = g.K, nt = K / BK;
;     unsigned voffA[2], voffB[2];
; #pragma unroll
;     for (int i = 0; i < 2; ++i) { int R, C; stage_rc(tid * 16 + i * 8192, R, C); const int Rb = Epi::PERM ? ((R & ~31) + perm32(R & 31)) : R;
;         voffA[i] = (unsigned)(R * g.lda + C) * 2u; voffB[i] = (unsigned)(Rb * g.ldb + C) * 2u; }
;     const size_t kstep = (size_t)(BK * 2);
;     const size_t hstepA = (size_t)HALF * g.lda * 2, hstepB = (size_t)HALF * g.ldb * 2;
;     const size_t tstepA = 2 * hstepA, tstepB = 2 * hstepB;
;     const unsigned ldsw = (unsigned)wid * 1024u;
;     const int aoff = lds_byte(wr * 64 + fr, fq * 8), boff = lds_byte(wc * 32 + fr, fq * 8);
;     ...
;     Unit cur, nxt; int ui = 0;
;     if (!S.next(0, cur)) return;
;     f32x4 acc[2][2][4][2];
; #pragma unroll
;     for (int a = 0; a < 2; ++a)
; #pragma unroll
;         for (int b = 0; b < 2; ++b)
; #pragma unroll
;             for (int m = 0; m < 4; ++m)
; #pragma unroll
;                 for (int n = 0; n < 2; ++n) acc[a][b][m][n] = (f32x4){0.f, 0.f, 0.f, 0.f};
;     bf16x8 At[4][2], B0[2][2], B1[2][2];
;     const char* cA = (const char*)(g.A + (size_t)cur.g * g.gA) + (size_t)cur.pm * tstepA; const char* cB = (const char*)(g.Bt + (size_t)cur.g * g.gB) + (size_t)cur.pn * tstepB;
;     PG8_STAGE(PG8_SB(0, 0), cB, voffB); PG8_STAGE(PG8_SB(0, 1), cB + hstepB, voffB); PG8_STAGE(PG8_SA(0, 0), cA, voffA); PG8_STAGE(PG8_SA(0, 1), cA + hstepA, voffA);
;     if (wr == 1) PG8_BAR;
.LBB0_544:
	s_andn2_b64 vcc, exec, s[0:1]
	s_cbranch_vccnz .LBB0_601
	s_and_b32 s101, s100, 1
	s_mul_i32 s101, s101, 0xa00
	s_add_i32 s101, s101, s81
	s_bitcmp1_b32 s100, 0
	s_cbranch_scc0 .Ldef_entry_done
	v_readlane_b32 s0, v254, 17
	v_readlane_b32 s1, v254, 50
	v_readlane_b32 s12, v254, 52
	s_nop 1
	v_writelane_b32 v255, s0, 40
	v_writelane_b32 v255, s1, 41
	v_writelane_b32 v255, s12, 42
	v_readlane_b32 s0, v254, 53
	v_readlane_b32 s1, v254, 55
	v_readlane_b32 s12, v254, 56
	s_nop 1
	v_writelane_b32 v255, s0, 43
	v_writelane_b32 v255, s1, 44
	v_writelane_b32 v255, s12, 45
	v_readlane_b32 s0, v254, 57
	v_readlane_b32 s1, v254, 58
	v_readlane_b32 s12, v254, 59
	s_nop 1
	v_writelane_b32 v255, s0, 46
	v_writelane_b32 v255, s1, 47
	v_writelane_b32 v255, s12, 48
	v_readlane_b32 s0, v254, 60
	s_nop 1
	v_writelane_b32 v255, s0, 49
	s_and_b32 s0, s81, 7
	s_lshl_b32 s0, s0, 3
	s_bfe_u32 s1, s81, 0x30003
	s_or_b32 s0, s0, s1
	s_lshr_b32 s1, s81, 6
	s_add_i32 s1, s1, 40
	s_nop 0
	v_writelane_b32 v254, s0, 50
	v_writelane_b32 v254, s1, 17
	s_lshl_b32 s0, s0, 19
	s_mov_b32 s12, 0
	s_nop 0
	v_writelane_b32 v254, s0, 52
	v_writelane_b32 v254, s12, 53
	s_lshl_b32 s1, s1, 19
	s_add_u32 s0, s84, s1
	s_addc_u32 s1, s85, 0
	s_nop 0
	v_writelane_b32 v254, s0, 57
	v_writelane_b32 v254, s1, 58
	s_add_u32 s12, s0, 0x40000
	s_addc_u32 vcc_lo, s1, 0
	s_nop 0
	v_writelane_b32 v254, s12, 55
	v_writelane_b32 v254, vcc_lo, 56
	s_add_u32 s12, s0, 0x40080
	s_addc_u32 vcc_lo, s1, 0
	s_nop 0
	v_writelane_b32 v254, s12, 59
	v_writelane_b32 v254, vcc_lo, 60
.Ldef_entry_done:
	v_readlane_b32 s0, v251, 37
	s_waitcnt vmcnt(0)
	v_mov_b32_e32 v6, v0
	v_readlane_b32 s1, v251, 38
	s_bitcmp1_b32 s100, 0
	s_cbranch_scc0 .Ldef_gate_done
	s_cmp_lt_u32 s81, 128
	s_cselect_b64 s[0:1], -1, 0
.Ldef_gate_done:
	s_andn2_b64 vcc, exec, s[0:1]
	v_readfirstlane_b32 s12, v6
	s_cbranch_vccnz .LBB0_601
	v_lshlrev_b32_e32 v2, 4, v6
	v_add_u32_e32 v3, 0x2000, v2
	v_ashrrev_i32_e32 v4, 31, v3
	v_lshrrev_b32_e32 v4, 22, v4
	v_add_u32_e32 v4, v3, v4
	v_ashrrev_i32_e32 v7, 10, v4
	v_mul_i32_i24_e32 v4, 0x400, v7
	v_sub_u32_e32 v3, v3, v4
	v_lshrrev_b32_e32 v4, 4, v3
	v_bitop3_b32 v3, v4, v3, 32 bitop3:0x6c
	v_readlane_b32 s0, v255, 32
	v_ashrrev_i32_e32 v4, 31, v3
	v_readlane_b32 s1, v255, 33
	v_lshrrev_b32_e32 v4, 26, v4
	s_and_b64 s[0:1], s[0:1], exec
	v_add_u32_e32 v4, v3, v4
	v_lshlrev_b32_e32 v5, 3, v7
	s_cselect_b32 s0, 0x2000000, 0
	v_readlane_b32 s1, v254, 24
	v_ashrrev_i32_e32 v8, 6, v4
	v_and_b32_e32 v5, -16, v5
	s_add_u32 s2, s1, s0
	v_readlane_b32 s0, v254, 25
	v_add_u32_e32 v5, v8, v5
	s_addc_u32 s4, s0, 0
	v_and_b32_e32 v9, 3, v8
	s_mov_b32 s0, 0x1fffe0
	v_lshrrev_b32_e32 v10, 2, v5
	v_lshlrev_b32_e32 v11, 1, v5
	v_and_b32_e32 v4, 0xc0, v4
	v_and_or_b32 v9, v5, s0, v9
	v_and_b32_e32 v10, 4, v10
	v_and_b32_e32 v11, 24, v11
	v_sub_u32_e32 v3, v3, v4
	v_or3_b32 v10, v9, v10, v11
	v_lshlrev_b32_e32 v9, 5, v7
	v_ashrrev_i16_sdwa v3, v250, sext(v3) dst_sel:DWORD dst_unused:UNUSED_PAD src0_sel:DWORD src1_sel:BYTE_0
	v_and_b32_e32 v11, 32, v9
	v_bfe_i32 v9, v3, 0, 16
	v_add_lshl_u32 v3, v11, v9, 1
	v_lshl_add_u32 v146, v10, 11, v3
	v_lshl_add_u32 v148, v5, 11, v3
	v_bfe_i32 v3, v6, 27, 1
	v_lshrrev_b32_e32 v3, 22, v3
	v_add_u32_e32 v3, v2, v3
	v_and_b32_e32 v3, 0xfffffc00, v3
	v_sub_u32_e32 v2, v2, v3
	v_lshrrev_b32_e32 v3, 4, v2
	v_bitop3_b32 v3, v3, v2, 32 bitop3:0x6c
	v_ashrrev_i32_e32 v2, 31, v2
	v_lshrrev_b32_e32 v2, 26, v2
	v_add_u32_e32 v2, v3, v2
	v_ashrrev_i32_e32 v10, 6, v2
	v_ashrrev_i32_e32 v2, 31, v6
	v_lshrrev_b32_e32 v2, 26, v2
	v_add_u32_e32 v2, v6, v2
	v_ashrrev_i32_e32 v11, 6, v2
	v_lshlrev_b32_e32 v2, 3, v11
	v_and_b32_e32 v2, -16, v2
	v_add_u32_e32 v2, v10, v2
	v_and_b32_e32 v4, 3, v10
	v_lshrrev_b32_e32 v5, 2, v2
	v_lshlrev_b32_e32 v12, 1, v2
	v_and_or_b32 v4, v2, s0, v4
	v_and_b32_e32 v5, 4, v5
	v_and_b32_e32 v12, 24, v12
	v_or3_b32 v4, v4, v5, v12
	v_mul_i32_i24_e32 v12, 64, v10
	v_sub_u32_e32 v3, v3, v12
	s_ashr_i32 s13, s12, 6
	v_lshlrev_b32_e32 v5, 5, v11
	v_ashrrev_i16_sdwa v3, v250, sext(v3) dst_sel:DWORD dst_unused:UNUSED_PAD src0_sel:DWORD src1_sel:BYTE_0
	s_lshl_b32 s5, s13, 10
	v_and_b32_e32 v5, 32, v5
	v_bfe_i32 v12, v3, 0, 16
	v_add_lshl_u32 v3, v5, v12, 1
	s_add_i32 s6, s5, 0
	v_readlane_b32 s0, v254, 57
	v_lshl_add_u32 v150, v4, 11, v3
	s_add_i32 m0, s6, 0x10000
	v_readlane_b32 s1, v254, 58
	s_ashr_i32 s14, s12, 8
	v_lshl_add_u32 v194, v2, 11, v3
	v_mov_b32_e32 v149, v195
	s_nop 1
	global_load_lds_dwordx4 v150, s[0:1]
	s_add_i32 m0, s6, 0x12000
	s_nop 0
	global_load_lds_dwordx4 v146, s[0:1]
	v_readlane_b32 s0, v254, 55
	s_add_i32 m0, s6, 0x14000
	v_readlane_b32 s1, v254, 56
	s_nop 4
	global_load_lds_dwordx4 v150, s[0:1]
	s_add_i32 m0, s6, 0x16000
	s_nop 0
	global_load_lds_dwordx4 v146, s[0:1]
	v_readlane_b32 s0, v254, 52
	v_readlane_b32 s1, v254, 53
	s_add_u32 s38, s2, s0
	s_addc_u32 s39, s4, s1
	s_add_i32 s7, s6, 0x2000
	s_mov_b32 m0, s6
	s_add_u32 s0, s38, 0x40000
	global_load_lds_dwordx4 v194, s[38:39]
	s_mov_b32 m0, s7
	s_addc_u32 s1, s39, 0
	s_add_i32 s8, s6, 0x4000
	global_load_lds_dwordx4 v148, s[38:39]
	s_mov_b32 m0, s8
	s_add_i32 s9, s6, 0x6000
	global_load_lds_dwordx4 v194, s[0:1]
	s_mov_b32 m0, s9
	s_cmp_eq_u32 s14, 1
	global_load_lds_dwordx4 v148, s[0:1]
	v_lshl_add_u64 v[2:3], s[38:39], 0, v[194:195]
	s_cselect_b64 s[0:1], -1, 0
	s_cmp_lg_u32 s14, 1
	v_lshl_add_u64 v[4:5], s[38:39], 0, v[148:149]
	s_cbranch_scc1 .LBB0_548
	s_barrier

;     __device__ bool next(int i, Unit& u) const {
;         const int ti = i / ng; u.g = i - ti * ng;
;         const long L = (long)ti * G + c; if (L >= nwg) return false;
;         int wgid = (int)L; { const int q = nwg / NXCD, r = nwg % NXCD, xcd = wgid % NXCD, off = wgid / NXCD; wgid = (xcd < r ? xcd * (q + 1) : r * (q + 1) + (xcd - r) * q) + off; }
;         const int nig = WGM * nN, gid = wgid / nig, fm = gid * WGM, gsz = (nM - fm) < WGM ? (nM - fm) : WGM;
;         u.pm = fm + ((wgid % nig) % gsz); u.pn = (wgid % nig) / gsz; return true;
; template <class Epi>
; __device__ __forceinline__ void gemm_phase(LAS unsigned char* lds, const Gemm g, const Order& S, const Epi& E) {
;     ...
;     for (;;) {
;         const bool has_next = S.next(ui + 1, nxt);
;         const char* nA = has_next ? (const char*)(g.A + (size_t)nxt.g * g.gA) + (size_t)nxt.pm * tstepA : cA; const char* nB = has_next ? (const char*)(g.Bt + (size_t)nxt.g * g.gB) + (size_t)nxt.pn * tstepB : cB;
.LBB0_550:
	s_andn2_b64 vcc, exec, s[36:37]
	s_mov_b32 s13, s44
	s_mov_b32 s14, s46
	s_mov_b64 s[50:51], s[48:49]
	s_mov_b64 s[38:39], s[30:31]
	s_cbranch_vccz .LBB0_600
	s_bitset1_b32 s100, 1
.LBB0_551:
	s_add_i32 s12, s12, 1
	s_mul_i32 s15, s12, s80
	s_mul_hi_u32 s16, s12, s94
	s_add_i32 s16, s16, s15
	s_mul_i32 s15, s12, s94
	s_add_u32 s30, s15, s101
	s_addc_u32 s31, s16, s83
	s_movk_i32 s15, 0xa00
	s_bitcmp1_b32 s100, 0
	s_cselect_b32 s15, 0xa80, s15
	v_mov_b32_e32 v2, s15
	v_mov_b32_e32 v3, 0
	v_cmp_ge_i64_e32 vcc, s[30:31], v[2:3]
	v_cmp_lt_i64_e64 s[36:37], s[30:31], v[2:3]
	s_cbranch_vccnz .LBB0_553
	s_ashr_i32 s15, s30, 31
	s_lshr_b32 s15, s15, 29
	s_add_i32 s15, s30, s15
	s_ashr_i32 s16, s15, 3
	s_and_b32 s15, s15, -8
	s_sub_i32 s15, s30, s15
	s_cmp_lt_i32 s15, 0
	s_movk_i32 s17, 0x151
	s_cselect_b32 s17, s17, 0x150
	s_mul_i32 s15, s15, s17
	s_add_i32 s15, s15, s16
	s_mul_hi_i32 s16, s15, 0x30c30c31
	s_lshr_b32 s17, s16, 31
	s_ashr_i32 s16, s16, 6
	s_add_i32 s16, s16, s17
	s_lshl_b32 s17, s16, 3
	s_sub_i32 s18, 64, s17
	s_min_i32 s18, s18, 8
	s_abs_i32 s19, s18
	v_cvt_f32_u32_e32 v2, s19
	s_sub_i32 s30, 0, s19
	s_mulk_i32 s16, 0x150
	s_sub_i32 s15, s15, s16
	v_rcp_iflag_f32_e32 v2, v2
	s_abs_i32 s16, s15
	s_xor_b32 s20, s15, s18
	s_ashr_i32 s20, s20, 31
	v_mul_f32_e32 v2, 0x4f7ffffe, v2
	v_cvt_u32_f32_e32 v2, v2
	s_nop 0
	v_readfirstlane_b32 s31, v2
	s_mul_i32 s30, s30, s31
	s_mul_hi_u32 s30, s31, s30
	s_add_i32 s31, s31, s30
	s_mul_hi_u32 s30, s16, s31
	s_mul_i32 s31, s30, s19
	s_sub_i32 s16, s16, s31
	s_add_i32 s44, s30, 1
	s_sub_i32 s31, s16, s19
	s_cmp_ge_u32 s16, s19
	s_cselect_b32 s30, s44, s30
	s_cselect_b32 s16, s31, s16
	s_add_i32 s31, s30, 1
	s_cmp_ge_u32 s16, s19
	s_cselect_b32 s16, s31, s30
	s_xor_b32 s16, s16, s20
	s_sub_i32 s44, s16, s20
	s_mul_i32 s16, s44, s18
	s_sub_i32 s15, s15, s16
	s_add_i32 s46, s17, s15

; #define PG8_STAGE(bufoff, gbase, voff) do { _Pragma("unroll") for (int _i = 0; _i < 2; ++_i) \
;         __builtin_amdgcn_global_load_lds((const unsigned*)((const char*)(gbase) + (voff)[_i]), (LAS unsigned*)(lds + (bufoff) + ldsw + _i * 8192), 16, 0, 0); } while (0)
; #define PG8_LDA(dst, b, h) do { _Pragma("unroll") for (int m = 0; m < 4; ++m) _Pragma("unroll") for (int k = 0; k < 2; ++k) dst[m][k] = *(const LAS bf16x8*)(lds + PG8_SA(b, h) + aoff + m * 2048 + k * 1024); } while (0)
; #define PG8_LDB(dst, b, h) do { _Pragma("unroll") for (int n = 0; n < 2; ++n) _Pragma("unroll") for (int k = 0; k < 2; ++k) dst[n][k] = *(const LAS bf16x8*)(lds + PG8_SB(b, h) + boff + n * 2048 + k * 1024); } while (0)
; #define PG8_MMA(ai, bj, At, Bt) do { __builtin_amdgcn_s_setprio(1); _Pragma("unroll") for (int m = 0; m < 4; ++m) _Pragma("unroll") for (int n = 0; n < 2; ++n) _Pragma("unroll") for (int k = 0; k < 2; ++k) \
;         acc[ai][bj][m][n] = __builtin_amdgcn_mfma_f32_16x16x32_bf16(Bt[n][k], At[m][k], acc[ai][bj][m][n], 0, 0, 0); __builtin_amdgcn_s_setprio(0); } while (0)
; #define PG8_WAIT_V(n) asm volatile("s_waitcnt vmcnt(" #n ")" ::: "memory")
; #define PG8_WAIT_L(n) asm volatile("s_waitcnt lgkmcnt(" #n ")" ::: "memory")
; #define PG8_BAR __builtin_amdgcn_s_barrier()
; #define PG8_SCHED __builtin_amdgcn_sched_barrier(0)
; template <class Epi>
; __device__ __forceinline__ void gemm_phase(LAS unsigned char* lds, const Gemm g, const Order& S, const Epi& E) {
;     ...
;         for (int t = 0; t < nt; t += 2) {
;             const bool last = (t == nt - 2);
;             const char* a1 = cA + (size_t)(t + 1) * kstep;
;             const char* a2 = last ? nA : cA + (size_t)(t + 2) * kstep; const char* b2 = last ? nB : cB + (size_t)(t + 2) * kstep;
;             const char* a3 = a2 + kstep; const char* b3 = b2 + kstep;
;             PG8_LDB(B0, 0, 0); PG8_LDB(B1, 0, 1); PG8_SCHED; PG8_LDA(At, 0, 0); PG8_STAGE(PG8_SA(1, 1), a1 + hstepA, voffA);
;             PG8_WAIT_V(8); PG8_WAIT_L(0); PG8_BAR; PG8_MMA(0, 0, At, B0); PG8_MMA(0, 1, At, B1); PG8_BAR; PG8_SCHED;
.LBB0_554:
	s_add_u32 s47, s38, 0xfffc0080
	s_addc_u32 s50, s39, -1
	s_add_i32 s54, 0, 0x10000
	s_cmp_eq_u32 s45, 12
	s_cselect_b32 s53, s15, s50
	s_cselect_b32 s52, s16, s47
	s_cselect_b32 s51, s17, s20
	s_cselect_b32 s50, s18, s19
	s_add_i32 s47, 0, 0x14000
	v_add_u32_e32 v86, s54, v163
	v_add_u32_e32 v160, s47, v163
	ds_read_b128 v[66:69], v86
	ds_read_b128 v[74:77], v86 offset:1024
	ds_read_b128 v[82:85], v86 offset:2048
	ds_read_b128 v[86:89], v86 offset:3072
	ds_read_b128 v[156:159], v160
	ds_read_b128 v[166:169], v160 offset:1024
	ds_read_b128 v[170:173], v160 offset:2048
	ds_read_b128 v[174:177], v160 offset:3072
	v_lshl_add_u64 v[160:161], s[38:39], 0, v[152:153]
	s_add_i32 m0, s6, 0xc000
	ds_read_b128 v[178:181], v165
	ds_read_b128 v[182:185], v165 offset:1024
	ds_read_b128 v[186:189], v165 offset:2048
	ds_read_b128 v[190:193], v165 offset:3072
	ds_read_b128 v[204:207], v165 offset:4096
	ds_read_b128 v[208:211], v165 offset:5120
	ds_read_b128 v[212:215], v165 offset:6144
	ds_read_b128 v[216:219], v165 offset:7168
	global_load_lds_dwordx4 v[160:161], off
	v_lshl_add_u64 v[160:161], s[38:39], 0, v[154:155]
	s_add_i32 m0, s6, 0xe000
	s_nop 0
	global_load_lds_dwordx4 v[160:161], off
	s_bitcmp1_b32 s100, 1
	s_cbranch_scc1 .Lxr1_LBB0554
	s_waitcnt vmcnt(8)
	s_branch .Lxb1_LBB0554

; #define PG8_STAGE(bufoff, gbase, voff) do { _Pragma("unroll") for (int _i = 0; _i < 2; ++_i) \
;         __builtin_amdgcn_global_load_lds((const unsigned*)((const char*)(gbase) + (voff)[_i]), (LAS unsigned*)(lds + (bufoff) + ldsw + _i * 8192), 16, 0, 0); } while (0)
; #define PG8_LDA(dst, b, h) do { _Pragma("unroll") for (int m = 0; m < 4; ++m) _Pragma("unroll") for (int k = 0; k < 2; ++k) dst[m][k] = *(const LAS bf16x8*)(lds + PG8_SA(b, h) + aoff + m * 2048 + k * 1024); } while (0)
; #define PG8_MMA(ai, bj, At, Bt) do { __builtin_amdgcn_s_setprio(1); _Pragma("unroll") for (int m = 0; m < 4; ++m) _Pragma("unroll") for (int n = 0; n < 2; ++n) _Pragma("unroll") for (int k = 0; k < 2; ++k) \
;         acc[ai][bj][m][n] = __builtin_amdgcn_mfma_f32_16x16x32_bf16(Bt[n][k], At[m][k], acc[ai][bj][m][n], 0, 0, 0); __builtin_amdgcn_s_setprio(0); } while (0)
; #define PG8_WAIT_V(n) asm volatile("s_waitcnt vmcnt(" #n ")" ::: "memory")
; #define PG8_WAIT_L(n) asm volatile("s_waitcnt lgkmcnt(" #n ")" ::: "memory")
; #define PG8_BAR __builtin_amdgcn_s_barrier()
; #define PG8_SCHED __builtin_amdgcn_sched_barrier(0)
; template <class Epi>
; __device__ __forceinline__ void gemm_phase(LAS unsigned char* lds, const Gemm g, const Order& S, const Epi& E) {
;     ...
;             PG8_WAIT_V(8); PG8_WAIT_L(0); PG8_BAR; PG8_MMA(0, 0, At, B0); PG8_MMA(0, 1, At, B1); PG8_BAR; PG8_SCHED;
;             PG8_LDA(At, 0, 1); PG8_STAGE(PG8_SB(0, 0), b2, voffB); PG8_STAGE(PG8_SB(0, 1), b2 + hstepB, voffB); PG8_STAGE(PG8_SA(0, 0), a2, voffA);
;             PG8_WAIT_V(8); PG8_WAIT_L(0); PG8_BAR; PG8_MMA(1, 0, At, B0); PG8_MMA(1, 1, At, B1); PG8_BAR; PG8_SCHED;
.Lxb1_LBB0554:
	s_waitcnt lgkmcnt(0)
	s_barrier
	s_setprio 1
	s_waitcnt lgkmcnt(0)
	v_mfma_f32_16x16x32_bf16 v[142:145], v[66:69], v[178:181], v[142:145]
	v_mfma_f32_16x16x32_bf16 v[138:141], v[82:85], v[178:181], v[138:141]
	v_mfma_f32_16x16x32_bf16 v[126:129], v[66:69], v[186:189], v[126:129]
	v_mfma_f32_16x16x32_bf16 v[122:125], v[82:85], v[186:189], v[122:125]
	v_mfma_f32_16x16x32_bf16 v[110:113], v[66:69], v[204:207], v[110:113]
	v_mfma_f32_16x16x32_bf16 v[106:109], v[82:85], v[204:207], v[106:109]
	v_mfma_f32_16x16x32_bf16 v[94:97], v[66:69], v[212:215], v[94:97]
	v_mfma_f32_16x16x32_bf16 v[90:93], v[82:85], v[212:215], v[90:93]
	v_mfma_f32_16x16x32_bf16 v[142:145], v[74:77], v[182:185], v[142:145]
	v_mfma_f32_16x16x32_bf16 v[138:141], v[86:89], v[182:185], v[138:141]
	v_mfma_f32_16x16x32_bf16 v[126:129], v[74:77], v[190:193], v[126:129]
	v_mfma_f32_16x16x32_bf16 v[122:125], v[86:89], v[190:193], v[122:125]
	v_mfma_f32_16x16x32_bf16 v[110:113], v[74:77], v[208:211], v[110:113]
	v_mfma_f32_16x16x32_bf16 v[106:109], v[86:89], v[208:211], v[106:109]
	v_mfma_f32_16x16x32_bf16 v[94:97], v[74:77], v[216:219], v[94:97]
	v_mfma_f32_16x16x32_bf16 v[90:93], v[86:89], v[216:219], v[90:93]
	s_setprio 0
	s_setprio 1
	v_mfma_f32_16x16x32_bf16 v[134:137], v[156:159], v[178:181], v[134:137]
	v_mfma_f32_16x16x32_bf16 v[130:133], v[170:173], v[178:181], v[130:133]
	v_mfma_f32_16x16x32_bf16 v[118:121], v[156:159], v[186:189], v[118:121]
	v_mfma_f32_16x16x32_bf16 v[114:117], v[170:173], v[186:189], v[114:117]
	v_mfma_f32_16x16x32_bf16 v[102:105], v[156:159], v[204:207], v[102:105]
	v_mfma_f32_16x16x32_bf16 v[98:101], v[170:173], v[204:207], v[98:101]
	v_mfma_f32_16x16x32_bf16 v[78:81], v[156:159], v[212:215], v[78:81]
	v_mfma_f32_16x16x32_bf16 v[70:73], v[170:173], v[212:215], v[70:73]
	v_mfma_f32_16x16x32_bf16 v[134:137], v[166:169], v[182:185], v[134:137]
	v_mfma_f32_16x16x32_bf16 v[130:133], v[174:177], v[182:185], v[130:133]
	v_mfma_f32_16x16x32_bf16 v[118:121], v[166:169], v[190:193], v[118:121]
	v_mfma_f32_16x16x32_bf16 v[114:117], v[174:177], v[190:193], v[114:117]
	v_mfma_f32_16x16x32_bf16 v[102:105], v[166:169], v[208:211], v[102:105]
	v_mfma_f32_16x16x32_bf16 v[98:101], v[174:177], v[208:211], v[98:101]
	v_mfma_f32_16x16x32_bf16 v[78:81], v[166:169], v[216:219], v[78:81]
	v_mfma_f32_16x16x32_bf16 v[70:73], v[174:177], v[216:219], v[70:73]
	s_setprio 0
	s_barrier
	s_add_i32 s54, s54, s5
	v_lshl_add_u64 v[160:161], s[50:51], 0, v[150:151]
	s_mov_b32 m0, s54
	ds_read_b128 v[178:181], v165 offset:16384
	ds_read_b128 v[182:185], v165 offset:17408
	ds_read_b128 v[186:189], v165 offset:18432
	ds_read_b128 v[190:193], v165 offset:19456
	ds_read_b128 v[204:207], v165 offset:20480
	ds_read_b128 v[208:211], v165 offset:21504
	ds_read_b128 v[212:215], v165 offset:22528
	ds_read_b128 v[216:219], v165 offset:23552
	global_load_lds_dwordx4 v[160:161], off
	s_add_i32 m0, s54, 0x2000
	s_add_u32 s54, s50, 0x40000
	v_lshl_add_u64 v[220:221], s[50:51], 0, v[146:147]
	s_addc_u32 s55, s51, 0
	s_add_i32 s47, s47, s5
	global_load_lds_dwordx4 v[220:221], off
	v_lshl_add_u64 v[222:223], s[54:55], 0, v[150:151]
	s_mov_b32 m0, s47
	v_lshl_add_u64 v[224:225], s[52:53], 0, v[148:149]
	global_load_lds_dwordx4 v[222:223], off
	v_lshl_add_u64 v[222:223], s[54:55], 0, v[146:147]
	s_add_i32 m0, s47, 0x2000
	s_nop 0
	global_load_lds_dwordx4 v[222:223], off
	v_lshl_add_u64 v[222:223], s[52:53], 0, v[194:195]
	s_mov_b32 m0, s6
	s_nop 0
	global_load_lds_dwordx4 v[222:223], off
	s_mov_b32 m0, s7
	s_nop 0
	global_load_lds_dwordx4 v[224:225], off
	s_bitcmp1_b32 s100, 1
	s_cbranch_scc1 .Lxr2_LBB0554
	s_waitcnt vmcnt(8)
	s_branch .Lxb2_LBB0554

; __global__ void __launch_bounds__(NTHR, 2) fwd_kernel(Params P) {
;     ...
;         const bool empty = (k == 0 && l == 1) || (k == 1) || (k == 7 && fuse);
;         if (ph + 1 < hi && !empty) { if (hi < lo) grid.sync(); else xcd_barrier(xb); }
.LBB0_758:
	v_readlane_b32 s6, v255, 31
	s_cmp_eq_u32 s6, 0
	s_cselect_b64 s[0:1], -1, 0
	s_sub_i32 s2, s88, 19
	s_cmp_lt_u32 s2, 19
	s_cselect_b64 s[4:5], -1, 0
	s_and_b64 s[0:1], s[4:5], s[0:1]
	s_cmp_eq_u32 s6, 1
	s_cselect_b64 s[4:5], -1, 0
	s_or_b64 s[0:1], s[4:5], s[0:1]
	s_cmp_eq_u32 s6, 7
	s_cselect_b64 s[4:5], -1, 0
	s_and_b64 s[4:5], s[90:91], s[4:5]
	s_or_b64 s[0:1], s[0:1], s[4:5]
	s_cmp_eq_u32 s6, 2
	s_cselect_b32 s101, 1, 0
	s_xor_b32 s100, s100, s101
	s_and_b32 s4, s101, s100
	s_andn2_b32 s101, s101, s100
	s_sub_i32 s88, s88, s4
	s_add_i32 s88, s88, 1
	s_cmp_ge_i32 s88, s89
	s_cselect_b64 s[4:5], -1, 0
	s_or_b64 s[0:1], s[4:5], s[0:1]
	s_cmp_eq_u32 s101, 1
	s_cbranch_scc0 .Ldef_tail_done
	s_mov_b64 s[0:1], -1
	v_readlane_b32 s2, v255, 40
	v_readlane_b32 s4, v255, 41
	v_readlane_b32 s5, v255, 42
	s_nop 1
	v_writelane_b32 v254, s2, 17
	v_writelane_b32 v254, s4, 50
	v_writelane_b32 v254, s5, 52
	v_readlane_b32 s2, v255, 43
	v_readlane_b32 s4, v255, 44
	v_readlane_b32 s5, v255, 45
	s_nop 1
	v_writelane_b32 v254, s2, 53
	v_writelane_b32 v254, s4, 55
	v_writelane_b32 v254, s5, 56
	v_readlane_b32 s2, v255, 46
	v_readlane_b32 s4, v255, 47
	v_readlane_b32 s5, v255, 48
	s_nop 1
	v_writelane_b32 v254, s2, 57
	v_writelane_b32 v254, s4, 58
	v_writelane_b32 v254, s5, 59
	v_readlane_b32 s2, v255, 49
	s_nop 1
	v_writelane_b32 v254, s2, 60
.Ldef_tail_done:
	s_and_b64 vcc, exec, s[0:1]
	s_cbranch_vccz .LBB0_759
	s_getpc_b64 s[98:99]
